# attention tile loop stagger: waves 4-7 sleep 8x64 cycles at each tile head so SIMD partners alternate MFMA and softmax phases (on top of the FFT chain stagger)
# baseline (speedup 1.0000x reference)
; __device__ __forceinline__ void attn_mfma(LAS unsigned char* lds, int layer, int G, const int wave_s) {
;     ...
;         for (int i = 0; i < NT; ++i) {
;             const int bf = i & 1;
;             f32x16 p0, p1;
; #pragma unroll
;             for (int r = 0; r < 16; ++r) { p0[r] = 0.f; p1[r] = 0.f; }
.LBB0_796:
	s_cmpk_lt_u32 s1, 0x100
	s_cbranch_scc1 .Lat_ns
	s_sleep 8
